# epirope: hand-written in-proj epilogue for rotary tiles (16 table loads up front, counted vmcnt, shared entries for both halves) on top of v41 set
# speedup vs baseline: 1.0154x; 1.0132x over previous
; #define GAS __attribute__((address_space(1)))
;     __device__ __forceinline__ void operator()(const f32x4 (&acc)[2][2][4][2], const Unit& u, int wr, int wc, int fr, int fq, const PG8_LAS float* tab) const {
;         const int pn = u.pn; const bool is_rope = (pn < 4) || (pn == 8); const bool is_z = (pn >= 18); const float qs = (pn < 4) ? 0.125f : 1.0f;
; #pragma unroll
;         for (int ai = 0; ai < 2; ++ai)
; #pragma unroll
;             for (int m = 0; m < 4; ++m) {
;                 const int row = u.pm * BM + ai * HALF + wr * 64 + m * 16 + fr;
;                 const float rs = rsqrtf(tab[ai * HALF + wr * 64 + m * 16 + fr] * (1.0f / 2048.0f) + 1e-6f);
;                 const int pos = row < 16384 ? (row & 8191) : (row - 16384);
;                 GAS bf16_t* rowp = (GAS bf16_t*)P + (size_t)row * 5120;
;                 if (is_z) {
;                     const f32x4 z0 = (acc[ai][0][m][0] * rs) * (acc[ai][1][m][0] * rs), z1 = (acc[ai][0][m][1] * rs) * (acc[ai][1][m][1] * rs);
;                     u32x4 w; w.x = cvt_pk_bf16(z0[0], z0[1]); w.y = cvt_pk_bf16(z0[2], z0[3]); w.z = cvt_pk_bf16(z1[0], z1[1]); w.w = cvt_pk_bf16(z1[2], z1[3]);
;                     *(GAS u32x4*)(rowp + 4608 + (pn - 18) * 128 + wc * 32 + 8 * fq) = w;
;                     continue;
;                 }
; #pragma unroll
;                 for (int bj = 0; bj < 2; ++bj) {
;                     const int col0 = pn * BM + bj * HALF + wc * 32 + 8 * fq;
;                     f32x4 v0 = acc[ai][bj][m][0] * rs, v1 = acc[ai][bj][m][1] * rs;
;                     if (is_rope) {
;                         const GAS f32x4* rp = (const GAS f32x4*)((const GAS f32x2*)rope + (size_t)pos * 32 + ((col0 & 63) >> 1));
;                         const f32x4 cs0 = rp[0], cs1 = rp[1];
;                         f32x4 o0, o1;
;                         o0[0] = v0[0] * cs0[0] - v0[1] * cs0[1]; o0[1] = v0[1] * cs0[0] + v0[0] * cs0[1];
;                         o0[2] = v0[2] * cs0[2] - v0[3] * cs0[3]; o0[3] = v0[3] * cs0[2] + v0[2] * cs0[3];
;                         o1[0] = v1[0] * cs1[0] - v1[1] * cs1[1]; o1[1] = v1[1] * cs1[0] + v1[0] * cs1[1];
;                         o1[2] = v1[2] * cs1[2] - v1[3] * cs1[3]; o1[3] = v1[3] * cs1[2] + v1[2] * cs1[3];
;                         v0 = o0 * qs; v1 = o1 * qs;
;                     }
;                     {
.LBB0_348:
	s_cmp_lt_i32 s0, 4
	s_cbranch_scc1 .Lei_rope
	s_cmp_eq_u32 s0, 8
	s_cbranch_scc0 .Lei_compiler
.Lei_rope:
	s_and_b32 s4, s3, 1
	s_lshl_b32 s4, s4, 10
	v_add_u32_e32 v231, s4, v172
	ds_read_b32 v154, v231 offset:0
	ds_read_b32 v156, v231 offset:64
	ds_read_b32 v158, v231 offset:128
	ds_read_b32 v160, v231 offset:192
	ds_read_b32 v155, v231 offset:512
	ds_read_b32 v157, v231 offset:576
	ds_read_b32 v159, v231 offset:640
	ds_read_b32 v161, v231 offset:704
	s_cmp_lt_i32 s0, 4
	s_cselect_b32 s4, 0x3e000000, 1.0
	v_mov_b32_e32 v234, s4
	v_mov_b32_e32 v235, s4
	s_cmp_lt_i32 s1, 64
	s_cselect_b32 s4, 31, 63
	s_and_b32 s4, s1, s4
	s_lshl_b32 s4, s4, 16
	s_add_u32 s28, s14, s4
	s_addc_u32 s29, s15, 0
	v_lshlrev_b32_e32 v232, 2, v173
	v_and_b32_e32 v232, 0xe0, v232
	v_lshl_add_u32 v232, v1, 8, v232
	s_mov_b64 s[10:11], s[28:29]
	global_load_dwordx4 v[176:179], v232, s[10:11]
	global_load_dwordx4 v[180:183], v232, s[10:11] offset:16
	s_add_u32 s10, s28, 0x1000
	s_addc_u32 s11, s29, 0
	global_load_dwordx4 v[184:187], v232, s[10:11]
	global_load_dwordx4 v[188:191], v232, s[10:11] offset:16
	s_add_u32 s10, s28, 0x2000
	s_addc_u32 s11, s29, 0
	global_load_dwordx4 v[192:195], v232, s[10:11]
	global_load_dwordx4 v[196:199], v232, s[10:11] offset:16
	s_add_u32 s10, s28, 0x3000
	s_addc_u32 s11, s29, 0
	global_load_dwordx4 v[200:203], v232, s[10:11]
	global_load_dwordx4 v[204:207], v232, s[10:11] offset:16
	s_add_u32 s10, s28, 0x8000
	s_addc_u32 s11, s29, 0
	global_load_dwordx4 v[208:211], v232, s[10:11]
	global_load_dwordx4 v[212:215], v232, s[10:11] offset:16
	s_add_u32 s10, s28, 0x9000
	s_addc_u32 s11, s29, 0
	global_load_dwordx4 v[216:219], v232, s[10:11]
	global_load_dwordx4 v[220:223], v232, s[10:11] offset:16
	s_add_u32 s10, s28, 0xa000
	s_addc_u32 s11, s29, 0
	global_load_dwordx4 v[224:227], v232, s[10:11]
	global_load_dwordx4 v[240:243], v232, s[10:11] offset:16
	s_add_u32 s10, s28, 0xb000
	s_addc_u32 s11, s29, 0
	global_load_dwordx4 v[244:247], v232, s[10:11]
	global_load_dwordx4 v[248:251], v232, s[10:11] offset:16
	s_mul_i32 s4, s1, 0x280000
	s_lshl_b32 s5, s0, 9
	s_add_u32 s4, s4, s5
	s_add_u32 s6, s86, s4
	s_addc_u32 s7, s87, 0
	v_mul_u32_u24_e32 v230, 0x2800, v1
	v_lshl_add_u32 v230, v173, 1, v230
	s_waitcnt lgkmcnt(0)
	v_fmamk_f32 v154, v154, 0x3a000000, v236
	v_fmamk_f32 v156, v156, 0x3a000000, v236
	v_fmamk_f32 v158, v158, 0x3a000000, v236
	v_fmamk_f32 v160, v160, 0x3a000000, v236
	v_fmamk_f32 v155, v155, 0x3a000000, v236
	v_fmamk_f32 v157, v157, 0x3a000000, v236
	v_fmamk_f32 v159, v159, 0x3a000000, v236
	v_fmamk_f32 v161, v161, 0x3a000000, v236
	v_rsq_f32_e32 v154, v154
	v_rsq_f32_e32 v156, v156
	v_rsq_f32_e32 v158, v158
	v_rsq_f32_e32 v160, v160
	v_rsq_f32_e32 v155, v155
	v_rsq_f32_e32 v157, v157
	v_rsq_f32_e32 v159, v159
	v_rsq_f32_e32 v161, v161
	s_mov_b64 s[10:11], s[6:7]
	v_pk_mul_f32 v[126:127], v[126:127], v[154:155] op_sel_hi:[1,0]
	v_pk_mul_f32 v[128:129], v[128:129], v[154:155] op_sel_hi:[1,0]
	v_pk_mul_f32 v[122:123], v[122:123], v[154:155] op_sel_hi:[1,0]
	v_pk_mul_f32 v[124:125], v[124:125], v[154:155] op_sel_hi:[1,0]
	v_pk_mul_f32 v[118:119], v[118:119], v[154:155] op_sel_hi:[1,0]
	v_pk_mul_f32 v[120:121], v[120:121], v[154:155] op_sel_hi:[1,0]
	v_pk_mul_f32 v[114:115], v[114:115], v[154:155] op_sel_hi:[1,0]
	v_pk_mul_f32 v[116:117], v[116:117], v[154:155] op_sel_hi:[1,0]
	s_waitcnt vmcnt(14)
	v_pk_mul_f32 v[162:163], v[126:127], v[176:177] op_sel:[1,1] op_sel_hi:[0,1]
	v_pk_fma_f32 v[126:127], v[126:127], v[176:177], v[162:163] op_sel_hi:[1,0,1] neg_lo:[0,0,1]
	v_pk_mul_f32 v[126:127], v[126:127], v[234:235]
	v_pk_mul_f32 v[162:163], v[128:129], v[178:179] op_sel:[1,1] op_sel_hi:[0,1]
	v_pk_fma_f32 v[128:129], v[128:129], v[178:179], v[162:163] op_sel_hi:[1,0,1] neg_lo:[0,0,1]
	v_pk_mul_f32 v[128:129], v[128:129], v[234:235]
	v_pk_mul_f32 v[162:163], v[122:123], v[180:181] op_sel:[1,1] op_sel_hi:[0,1]
	v_pk_fma_f32 v[122:123], v[122:123], v[180:181], v[162:163] op_sel_hi:[1,0,1] neg_lo:[0,0,1]
	v_pk_mul_f32 v[122:123], v[122:123], v[234:235]
	v_pk_mul_f32 v[162:163], v[124:125], v[182:183] op_sel:[1,1] op_sel_hi:[0,1]
	v_pk_fma_f32 v[124:125], v[124:125], v[182:183], v[162:163] op_sel_hi:[1,0,1] neg_lo:[0,0,1]
	v_pk_mul_f32 v[124:125], v[124:125], v[234:235]
	v_cvt_pk_bf16_f32 v164, v126, v127
	v_cvt_pk_bf16_f32 v165, v128, v129
	v_cvt_pk_bf16_f32 v166, v122, v123
	v_cvt_pk_bf16_f32 v167, v124, v125
	global_store_dwordx4 v230, v[164:167], s[10:11] offset:0
	v_pk_mul_f32 v[162:163], v[118:119], v[176:177] op_sel:[1,1] op_sel_hi:[0,1]
	v_pk_fma_f32 v[118:119], v[118:119], v[176:177], v[162:163] op_sel_hi:[1,0,1] neg_lo:[0,0,1]
	v_pk_mul_f32 v[118:119], v[118:119], v[234:235]
	v_pk_mul_f32 v[162:163], v[120:121], v[178:179] op_sel:[1,1] op_sel_hi:[0,1]
	v_pk_fma_f32 v[120:121], v[120:121], v[178:179], v[162:163] op_sel_hi:[1,0,1] neg_lo:[0,0,1]
	v_pk_mul_f32 v[120:121], v[120:121], v[234:235]
	v_pk_mul_f32 v[162:163], v[114:115], v[180:181] op_sel:[1,1] op_sel_hi:[0,1]
	v_pk_fma_f32 v[114:115], v[114:115], v[180:181], v[162:163] op_sel_hi:[1,0,1] neg_lo:[0,0,1]
	v_pk_mul_f32 v[114:115], v[114:115], v[234:235]
	v_pk_mul_f32 v[162:163], v[116:117], v[182:183] op_sel:[1,1] op_sel_hi:[0,1]
	v_pk_fma_f32 v[116:117], v[116:117], v[182:183], v[162:163] op_sel_hi:[1,0,1] neg_lo:[0,0,1]
	v_pk_mul_f32 v[116:117], v[116:117], v[234:235]
	v_cvt_pk_bf16_f32 v168, v118, v119
	v_cvt_pk_bf16_f32 v169, v120, v121
	v_cvt_pk_bf16_f32 v170, v114, v115
	v_cvt_pk_bf16_f32 v171, v116, v117
	global_store_dwordx4 v230, v[168:171], s[10:11] offset:256
	s_add_u32 s10, s6, 0x28000
	s_addc_u32 s11, s7, 0
	v_pk_mul_f32 v[110:111], v[110:111], v[156:157] op_sel_hi:[1,0]
	v_pk_mul_f32 v[112:113], v[112:113], v[156:157] op_sel_hi:[1,0]
	v_pk_mul_f32 v[106:107], v[106:107], v[156:157] op_sel_hi:[1,0]
	v_pk_mul_f32 v[108:109], v[108:109], v[156:157] op_sel_hi:[1,0]
	v_pk_mul_f32 v[102:103], v[102:103], v[156:157] op_sel_hi:[1,0]
	v_pk_mul_f32 v[104:105], v[104:105], v[156:157] op_sel_hi:[1,0]
	v_pk_mul_f32 v[98:99], v[98:99], v[156:157] op_sel_hi:[1,0]
	v_pk_mul_f32 v[100:101], v[100:101], v[156:157] op_sel_hi:[1,0]
	s_waitcnt vmcnt(14)
; #define GAS __attribute__((address_space(1)))
; __device__ __forceinline__ unsigned cvt_pk_bf16(float lo, float hi) { unsigned r; asm volatile("v_cvt_pk_bf16_f32 %0, %1, %2" : "=v"(r) : "v"(lo), "v"(hi)); return r; }
;     __device__ __forceinline__ void operator()(const f32x4 (&acc)[2][2][4][2], const Unit& u, int wr, int wc, int fr, int fq, const PG8_LAS float* tab) const {
;     ...
;                     f32x4 v0 = acc[ai][bj][m][0] * rs, v1 = acc[ai][bj][m][1] * rs;
;                     if (is_rope) {
;                         const GAS f32x4* rp = (const GAS f32x4*)((const GAS f32x2*)rope + (size_t)pos * 32 + ((col0 & 63) >> 1));
;                         const f32x4 cs0 = rp[0], cs1 = rp[1];
;                         f32x4 o0, o1;
;                         o0[0] = v0[0] * cs0[0] - v0[1] * cs0[1]; o0[1] = v0[1] * cs0[0] + v0[0] * cs0[1];
;                         o0[2] = v0[2] * cs0[2] - v0[3] * cs0[3]; o0[3] = v0[3] * cs0[2] + v0[2] * cs0[3];
;                         o1[0] = v1[0] * cs1[0] - v1[1] * cs1[1]; o1[1] = v1[1] * cs1[0] + v1[0] * cs1[1];
;                         o1[2] = v1[2] * cs1[2] - v1[3] * cs1[3]; o1[3] = v1[3] * cs1[2] + v1[2] * cs1[3];
;                         v0 = o0 * qs; v1 = o1 * qs;
;                     }
;                     {
;                         u32x4 w; w.x = cvt_pk_bf16(v0[0], v0[1]); w.y = cvt_pk_bf16(v0[2], v0[3]); w.z = cvt_pk_bf16(v1[0], v1[1]); w.w = cvt_pk_bf16(v1[2], v1[3]);
;                         *(GAS u32x4*)(rowp + col0) = w;
;                     }
	v_pk_mul_f32 v[162:163], v[110:111], v[184:185] op_sel:[1,1] op_sel_hi:[0,1]
	v_pk_fma_f32 v[110:111], v[110:111], v[184:185], v[162:163] op_sel_hi:[1,0,1] neg_lo:[0,0,1]
	v_pk_mul_f32 v[110:111], v[110:111], v[234:235]
	v_pk_mul_f32 v[162:163], v[112:113], v[186:187] op_sel:[1,1] op_sel_hi:[0,1]
	v_pk_fma_f32 v[112:113], v[112:113], v[186:187], v[162:163] op_sel_hi:[1,0,1] neg_lo:[0,0,1]
	v_pk_mul_f32 v[112:113], v[112:113], v[234:235]
	v_pk_mul_f32 v[162:163], v[106:107], v[188:189] op_sel:[1,1] op_sel_hi:[0,1]
	v_pk_fma_f32 v[106:107], v[106:107], v[188:189], v[162:163] op_sel_hi:[1,0,1] neg_lo:[0,0,1]
	v_pk_mul_f32 v[106:107], v[106:107], v[234:235]
	v_pk_mul_f32 v[162:163], v[108:109], v[190:191] op_sel:[1,1] op_sel_hi:[0,1]
	v_pk_fma_f32 v[108:109], v[108:109], v[190:191], v[162:163] op_sel_hi:[1,0,1] neg_lo:[0,0,1]
	v_pk_mul_f32 v[108:109], v[108:109], v[234:235]
	v_cvt_pk_bf16_f32 v164, v110, v111
	v_cvt_pk_bf16_f32 v165, v112, v113
	v_cvt_pk_bf16_f32 v166, v106, v107
	v_cvt_pk_bf16_f32 v167, v108, v109
	global_store_dwordx4 v230, v[164:167], s[10:11] offset:0
	v_pk_mul_f32 v[162:163], v[102:103], v[184:185] op_sel:[1,1] op_sel_hi:[0,1]
	v_pk_fma_f32 v[102:103], v[102:103], v[184:185], v[162:163] op_sel_hi:[1,0,1] neg_lo:[0,0,1]
	v_pk_mul_f32 v[102:103], v[102:103], v[234:235]
	v_pk_mul_f32 v[162:163], v[104:105], v[186:187] op_sel:[1,1] op_sel_hi:[0,1]
	v_pk_fma_f32 v[104:105], v[104:105], v[186:187], v[162:163] op_sel_hi:[1,0,1] neg_lo:[0,0,1]
	v_pk_mul_f32 v[104:105], v[104:105], v[234:235]
	v_pk_mul_f32 v[162:163], v[98:99], v[188:189] op_sel:[1,1] op_sel_hi:[0,1]
	v_pk_fma_f32 v[98:99], v[98:99], v[188:189], v[162:163] op_sel_hi:[1,0,1] neg_lo:[0,0,1]
	v_pk_mul_f32 v[98:99], v[98:99], v[234:235]
	v_pk_mul_f32 v[162:163], v[100:101], v[190:191] op_sel:[1,1] op_sel_hi:[0,1]
	v_pk_fma_f32 v[100:101], v[100:101], v[190:191], v[162:163] op_sel_hi:[1,0,1] neg_lo:[0,0,1]
	v_pk_mul_f32 v[100:101], v[100:101], v[234:235]
	v_cvt_pk_bf16_f32 v168, v102, v103
	v_cvt_pk_bf16_f32 v169, v104, v105
	v_cvt_pk_bf16_f32 v170, v98, v99
	v_cvt_pk_bf16_f32 v171, v100, v101
	global_store_dwordx4 v230, v[168:171], s[10:11] offset:256
	s_add_u32 s10, s6, 0x50000
	s_addc_u32 s11, s7, 0
	v_pk_mul_f32 v[94:95], v[94:95], v[158:159] op_sel_hi:[1,0]
	v_pk_mul_f32 v[96:97], v[96:97], v[158:159] op_sel_hi:[1,0]
	v_pk_mul_f32 v[90:91], v[90:91], v[158:159] op_sel_hi:[1,0]
	v_pk_mul_f32 v[92:93], v[92:93], v[158:159] op_sel_hi:[1,0]
	v_pk_mul_f32 v[86:87], v[86:87], v[158:159] op_sel_hi:[1,0]
	v_pk_mul_f32 v[88:89], v[88:89], v[158:159] op_sel_hi:[1,0]
	v_pk_mul_f32 v[82:83], v[82:83], v[158:159] op_sel_hi:[1,0]
	v_pk_mul_f32 v[84:85], v[84:85], v[158:159] op_sel_hi:[1,0]
	s_waitcnt vmcnt(14)
	v_pk_mul_f32 v[162:163], v[94:95], v[192:193] op_sel:[1,1] op_sel_hi:[0,1]
	v_pk_fma_f32 v[94:95], v[94:95], v[192:193], v[162:163] op_sel_hi:[1,0,1] neg_lo:[0,0,1]
	v_pk_mul_f32 v[94:95], v[94:95], v[234:235]
	v_pk_mul_f32 v[162:163], v[96:97], v[194:195] op_sel:[1,1] op_sel_hi:[0,1]
	v_pk_fma_f32 v[96:97], v[96:97], v[194:195], v[162:163] op_sel_hi:[1,0,1] neg_lo:[0,0,1]
	v_pk_mul_f32 v[96:97], v[96:97], v[234:235]
	v_pk_mul_f32 v[162:163], v[90:91], v[196:197] op_sel:[1,1] op_sel_hi:[0,1]
	v_pk_fma_f32 v[90:91], v[90:91], v[196:197], v[162:163] op_sel_hi:[1,0,1] neg_lo:[0,0,1]
	v_pk_mul_f32 v[90:91], v[90:91], v[234:235]
	v_pk_mul_f32 v[162:163], v[92:93], v[198:199] op_sel:[1,1] op_sel_hi:[0,1]
	v_pk_fma_f32 v[92:93], v[92:93], v[198:199], v[162:163] op_sel_hi:[1,0,1] neg_lo:[0,0,1]
	v_pk_mul_f32 v[92:93], v[92:93], v[234:235]
	v_cvt_pk_bf16_f32 v164, v94, v95
	v_cvt_pk_bf16_f32 v165, v96, v97
	v_cvt_pk_bf16_f32 v166, v90, v91
	v_cvt_pk_bf16_f32 v167, v92, v93
	global_store_dwordx4 v230, v[164:167], s[10:11] offset:0
	v_pk_mul_f32 v[162:163], v[86:87], v[192:193] op_sel:[1,1] op_sel_hi:[0,1]
	v_pk_fma_f32 v[86:87], v[86:87], v[192:193], v[162:163] op_sel_hi:[1,0,1] neg_lo:[0,0,1]
	v_pk_mul_f32 v[86:87], v[86:87], v[234:235]
	v_pk_mul_f32 v[162:163], v[88:89], v[194:195] op_sel:[1,1] op_sel_hi:[0,1]
	v_pk_fma_f32 v[88:89], v[88:89], v[194:195], v[162:163] op_sel_hi:[1,0,1] neg_lo:[0,0,1]
	v_pk_mul_f32 v[88:89], v[88:89], v[234:235]
	v_pk_mul_f32 v[162:163], v[82:83], v[196:197] op_sel:[1,1] op_sel_hi:[0,1]
	v_pk_fma_f32 v[82:83], v[82:83], v[196:197], v[162:163] op_sel_hi:[1,0,1] neg_lo:[0,0,1]
	v_pk_mul_f32 v[82:83], v[82:83], v[234:235]
	v_pk_mul_f32 v[162:163], v[84:85], v[198:199] op_sel:[1,1] op_sel_hi:[0,1]
	v_pk_fma_f32 v[84:85], v[84:85], v[198:199], v[162:163] op_sel_hi:[1,0,1] neg_lo:[0,0,1]
	v_pk_mul_f32 v[84:85], v[84:85], v[234:235]
	v_cvt_pk_bf16_f32 v168, v86, v87
	v_cvt_pk_bf16_f32 v169, v88, v89
	v_cvt_pk_bf16_f32 v170, v82, v83
	v_cvt_pk_bf16_f32 v171, v84, v85
	global_store_dwordx4 v230, v[168:171], s[10:11] offset:256
	s_add_u32 s10, s6, 0x78000
	s_addc_u32 s11, s7, 0
	v_pk_mul_f32 v[78:79], v[78:79], v[160:161] op_sel_hi:[1,0]
	v_pk_mul_f32 v[80:81], v[80:81], v[160:161] op_sel_hi:[1,0]
	v_pk_mul_f32 v[74:75], v[74:75], v[160:161] op_sel_hi:[1,0]
	v_pk_mul_f32 v[76:77], v[76:77], v[160:161] op_sel_hi:[1,0]
	v_pk_mul_f32 v[70:71], v[70:71], v[160:161] op_sel_hi:[1,0]
	v_pk_mul_f32 v[72:73], v[72:73], v[160:161] op_sel_hi:[1,0]
	v_pk_mul_f32 v[66:67], v[66:67], v[160:161] op_sel_hi:[1,0]
	v_pk_mul_f32 v[68:69], v[68:69], v[160:161] op_sel_hi:[1,0]
	s_waitcnt vmcnt(14)
; #define GAS __attribute__((address_space(1)))
; __device__ __forceinline__ unsigned cvt_pk_bf16(float lo, float hi) { unsigned r; asm volatile("v_cvt_pk_bf16_f32 %0, %1, %2" : "=v"(r) : "v"(lo), "v"(hi)); return r; }
;     __device__ __forceinline__ void operator()(const f32x4 (&acc)[2][2][4][2], const Unit& u, int wr, int wc, int fr, int fq, const PG8_LAS float* tab) const {
;     ...
;                     f32x4 v0 = acc[ai][bj][m][0] * rs, v1 = acc[ai][bj][m][1] * rs;
;                     if (is_rope) {
;                         const GAS f32x4* rp = (const GAS f32x4*)((const GAS f32x2*)rope + (size_t)pos * 32 + ((col0 & 63) >> 1));
;                         const f32x4 cs0 = rp[0], cs1 = rp[1];
;                         f32x4 o0, o1;
;                         o0[0] = v0[0] * cs0[0] - v0[1] * cs0[1]; o0[1] = v0[1] * cs0[0] + v0[0] * cs0[1];
;                         o0[2] = v0[2] * cs0[2] - v0[3] * cs0[3]; o0[3] = v0[3] * cs0[2] + v0[2] * cs0[3];
;                         o1[0] = v1[0] * cs1[0] - v1[1] * cs1[1]; o1[1] = v1[1] * cs1[0] + v1[0] * cs1[1];
;                         o1[2] = v1[2] * cs1[2] - v1[3] * cs1[3]; o1[3] = v1[3] * cs1[2] + v1[2] * cs1[3];
;                         v0 = o0 * qs; v1 = o1 * qs;
;                     }
;                     {
;                         u32x4 w; w.x = cvt_pk_bf16(v0[0], v0[1]); w.y = cvt_pk_bf16(v0[2], v0[3]); w.z = cvt_pk_bf16(v1[0], v1[1]); w.w = cvt_pk_bf16(v1[2], v1[3]);
;                         *(GAS u32x4*)(rowp + col0) = w;
;                     }
	v_pk_mul_f32 v[162:163], v[78:79], v[200:201] op_sel:[1,1] op_sel_hi:[0,1]
	v_pk_fma_f32 v[78:79], v[78:79], v[200:201], v[162:163] op_sel_hi:[1,0,1] neg_lo:[0,0,1]
	v_pk_mul_f32 v[78:79], v[78:79], v[234:235]
	v_pk_mul_f32 v[162:163], v[80:81], v[202:203] op_sel:[1,1] op_sel_hi:[0,1]
	v_pk_fma_f32 v[80:81], v[80:81], v[202:203], v[162:163] op_sel_hi:[1,0,1] neg_lo:[0,0,1]
	v_pk_mul_f32 v[80:81], v[80:81], v[234:235]
	v_pk_mul_f32 v[162:163], v[74:75], v[204:205] op_sel:[1,1] op_sel_hi:[0,1]
	v_pk_fma_f32 v[74:75], v[74:75], v[204:205], v[162:163] op_sel_hi:[1,0,1] neg_lo:[0,0,1]
	v_pk_mul_f32 v[74:75], v[74:75], v[234:235]
	v_pk_mul_f32 v[162:163], v[76:77], v[206:207] op_sel:[1,1] op_sel_hi:[0,1]
	v_pk_fma_f32 v[76:77], v[76:77], v[206:207], v[162:163] op_sel_hi:[1,0,1] neg_lo:[0,0,1]
	v_pk_mul_f32 v[76:77], v[76:77], v[234:235]
	v_cvt_pk_bf16_f32 v164, v78, v79
	v_cvt_pk_bf16_f32 v165, v80, v81
	v_cvt_pk_bf16_f32 v166, v74, v75
	v_cvt_pk_bf16_f32 v167, v76, v77
	global_store_dwordx4 v230, v[164:167], s[10:11] offset:0
	v_pk_mul_f32 v[162:163], v[70:71], v[200:201] op_sel:[1,1] op_sel_hi:[0,1]
	v_pk_fma_f32 v[70:71], v[70:71], v[200:201], v[162:163] op_sel_hi:[1,0,1] neg_lo:[0,0,1]
	v_pk_mul_f32 v[70:71], v[70:71], v[234:235]
	v_pk_mul_f32 v[162:163], v[72:73], v[202:203] op_sel:[1,1] op_sel_hi:[0,1]
	v_pk_fma_f32 v[72:73], v[72:73], v[202:203], v[162:163] op_sel_hi:[1,0,1] neg_lo:[0,0,1]
	v_pk_mul_f32 v[72:73], v[72:73], v[234:235]
	v_pk_mul_f32 v[162:163], v[66:67], v[204:205] op_sel:[1,1] op_sel_hi:[0,1]
	v_pk_fma_f32 v[66:67], v[66:67], v[204:205], v[162:163] op_sel_hi:[1,0,1] neg_lo:[0,0,1]
	v_pk_mul_f32 v[66:67], v[66:67], v[234:235]
	v_pk_mul_f32 v[162:163], v[68:69], v[206:207] op_sel:[1,1] op_sel_hi:[0,1]
	v_pk_fma_f32 v[68:69], v[68:69], v[206:207], v[162:163] op_sel_hi:[1,0,1] neg_lo:[0,0,1]
	v_pk_mul_f32 v[68:69], v[68:69], v[234:235]
	v_cvt_pk_bf16_f32 v168, v70, v71
	v_cvt_pk_bf16_f32 v169, v72, v73
	v_cvt_pk_bf16_f32 v170, v66, v67
	v_cvt_pk_bf16_f32 v171, v68, v69
	global_store_dwordx4 v230, v[168:171], s[10:11] offset:256
	v_mov_b32_e32 v154, v155
	v_mov_b32_e32 v156, v157
	v_mov_b32_e32 v158, v159
	v_mov_b32_e32 v160, v161
	s_add_u32 s10, s6, 0x140000
	s_addc_u32 s11, s7, 0
	v_pk_mul_f32 v[62:63], v[62:63], v[154:155] op_sel_hi:[1,0]
	v_pk_mul_f32 v[64:65], v[64:65], v[154:155] op_sel_hi:[1,0]
	v_pk_mul_f32 v[58:59], v[58:59], v[154:155] op_sel_hi:[1,0]
	v_pk_mul_f32 v[60:61], v[60:61], v[154:155] op_sel_hi:[1,0]
	v_pk_mul_f32 v[54:55], v[54:55], v[154:155] op_sel_hi:[1,0]
	v_pk_mul_f32 v[56:57], v[56:57], v[154:155] op_sel_hi:[1,0]
	v_pk_mul_f32 v[50:51], v[50:51], v[154:155] op_sel_hi:[1,0]
	v_pk_mul_f32 v[52:53], v[52:53], v[154:155] op_sel_hi:[1,0]
	s_waitcnt vmcnt(14)
	v_pk_mul_f32 v[162:163], v[62:63], v[208:209] op_sel:[1,1] op_sel_hi:[0,1]
	v_pk_fma_f32 v[62:63], v[62:63], v[208:209], v[162:163] op_sel_hi:[1,0,1] neg_lo:[0,0,1]
	v_pk_mul_f32 v[62:63], v[62:63], v[234:235]
	v_pk_mul_f32 v[162:163], v[64:65], v[210:211] op_sel:[1,1] op_sel_hi:[0,1]
	v_pk_fma_f32 v[64:65], v[64:65], v[210:211], v[162:163] op_sel_hi:[1,0,1] neg_lo:[0,0,1]
	v_pk_mul_f32 v[64:65], v[64:65], v[234:235]
	v_pk_mul_f32 v[162:163], v[58:59], v[212:213] op_sel:[1,1] op_sel_hi:[0,1]
	v_pk_fma_f32 v[58:59], v[58:59], v[212:213], v[162:163] op_sel_hi:[1,0,1] neg_lo:[0,0,1]
	v_pk_mul_f32 v[58:59], v[58:59], v[234:235]
	v_pk_mul_f32 v[162:163], v[60:61], v[214:215] op_sel:[1,1] op_sel_hi:[0,1]
	v_pk_fma_f32 v[60:61], v[60:61], v[214:215], v[162:163] op_sel_hi:[1,0,1] neg_lo:[0,0,1]
	v_pk_mul_f32 v[60:61], v[60:61], v[234:235]
	v_cvt_pk_bf16_f32 v164, v62, v63
	v_cvt_pk_bf16_f32 v165, v64, v65
	v_cvt_pk_bf16_f32 v166, v58, v59
	v_cvt_pk_bf16_f32 v167, v60, v61
	global_store_dwordx4 v230, v[164:167], s[10:11] offset:0
	v_pk_mul_f32 v[162:163], v[54:55], v[208:209] op_sel:[1,1] op_sel_hi:[0,1]
	v_pk_fma_f32 v[54:55], v[54:55], v[208:209], v[162:163] op_sel_hi:[1,0,1] neg_lo:[0,0,1]
	v_pk_mul_f32 v[54:55], v[54:55], v[234:235]
	v_pk_mul_f32 v[162:163], v[56:57], v[210:211] op_sel:[1,1] op_sel_hi:[0,1]
	v_pk_fma_f32 v[56:57], v[56:57], v[210:211], v[162:163] op_sel_hi:[1,0,1] neg_lo:[0,0,1]
	v_pk_mul_f32 v[56:57], v[56:57], v[234:235]
	v_pk_mul_f32 v[162:163], v[50:51], v[212:213] op_sel:[1,1] op_sel_hi:[0,1]
	v_pk_fma_f32 v[50:51], v[50:51], v[212:213], v[162:163] op_sel_hi:[1,0,1] neg_lo:[0,0,1]
	v_pk_mul_f32 v[50:51], v[50:51], v[234:235]
	v_pk_mul_f32 v[162:163], v[52:53], v[214:215] op_sel:[1,1] op_sel_hi:[0,1]
	v_pk_fma_f32 v[52:53], v[52:53], v[214:215], v[162:163] op_sel_hi:[1,0,1] neg_lo:[0,0,1]
	v_pk_mul_f32 v[52:53], v[52:53], v[234:235]
	v_cvt_pk_bf16_f32 v168, v54, v55
	v_cvt_pk_bf16_f32 v169, v56, v57
	v_cvt_pk_bf16_f32 v170, v50, v51
	v_cvt_pk_bf16_f32 v171, v52, v53
	global_store_dwordx4 v230, v[168:171], s[10:11] offset:256
	s_add_u32 s10, s6, 0x168000
	s_addc_u32 s11, s7, 0
	v_pk_mul_f32 v[46:47], v[46:47], v[156:157] op_sel_hi:[1,0]
	v_pk_mul_f32 v[48:49], v[48:49], v[156:157] op_sel_hi:[1,0]
	v_pk_mul_f32 v[42:43], v[42:43], v[156:157] op_sel_hi:[1,0]
	v_pk_mul_f32 v[44:45], v[44:45], v[156:157] op_sel_hi:[1,0]
	v_pk_mul_f32 v[38:39], v[38:39], v[156:157] op_sel_hi:[1,0]
	v_pk_mul_f32 v[40:41], v[40:41], v[156:157] op_sel_hi:[1,0]
	v_pk_mul_f32 v[34:35], v[34:35], v[156:157] op_sel_hi:[1,0]
	v_pk_mul_f32 v[36:37], v[36:37], v[156:157] op_sel_hi:[1,0]
	s_waitcnt vmcnt(14)
; #define GAS __attribute__((address_space(1)))
; __device__ __forceinline__ unsigned cvt_pk_bf16(float lo, float hi) { unsigned r; asm volatile("v_cvt_pk_bf16_f32 %0, %1, %2" : "=v"(r) : "v"(lo), "v"(hi)); return r; }
;     __device__ __forceinline__ void operator()(const f32x4 (&acc)[2][2][4][2], const Unit& u, int wr, int wc, int fr, int fq, const PG8_LAS float* tab) const {
;     ...
;                     f32x4 v0 = acc[ai][bj][m][0] * rs, v1 = acc[ai][bj][m][1] * rs;
;                     if (is_rope) {
;                         const GAS f32x4* rp = (const GAS f32x4*)((const GAS f32x2*)rope + (size_t)pos * 32 + ((col0 & 63) >> 1));
;                         const f32x4 cs0 = rp[0], cs1 = rp[1];
;                         f32x4 o0, o1;
;                         o0[0] = v0[0] * cs0[0] - v0[1] * cs0[1]; o0[1] = v0[1] * cs0[0] + v0[0] * cs0[1];
;                         o0[2] = v0[2] * cs0[2] - v0[3] * cs0[3]; o0[3] = v0[3] * cs0[2] + v0[2] * cs0[3];
;                         o1[0] = v1[0] * cs1[0] - v1[1] * cs1[1]; o1[1] = v1[1] * cs1[0] + v1[0] * cs1[1];
;                         o1[2] = v1[2] * cs1[2] - v1[3] * cs1[3]; o1[3] = v1[3] * cs1[2] + v1[2] * cs1[3];
;                         v0 = o0 * qs; v1 = o1 * qs;
;                     }
;                     {
;                         u32x4 w; w.x = cvt_pk_bf16(v0[0], v0[1]); w.y = cvt_pk_bf16(v0[2], v0[3]); w.z = cvt_pk_bf16(v1[0], v1[1]); w.w = cvt_pk_bf16(v1[2], v1[3]);
;                         *(GAS u32x4*)(rowp + col0) = w;
;                     }
	v_pk_mul_f32 v[162:163], v[46:47], v[216:217] op_sel:[1,1] op_sel_hi:[0,1]
	v_pk_fma_f32 v[46:47], v[46:47], v[216:217], v[162:163] op_sel_hi:[1,0,1] neg_lo:[0,0,1]
	v_pk_mul_f32 v[46:47], v[46:47], v[234:235]
	v_pk_mul_f32 v[162:163], v[48:49], v[218:219] op_sel:[1,1] op_sel_hi:[0,1]
	v_pk_fma_f32 v[48:49], v[48:49], v[218:219], v[162:163] op_sel_hi:[1,0,1] neg_lo:[0,0,1]
	v_pk_mul_f32 v[48:49], v[48:49], v[234:235]
	v_pk_mul_f32 v[162:163], v[42:43], v[220:221] op_sel:[1,1] op_sel_hi:[0,1]
	v_pk_fma_f32 v[42:43], v[42:43], v[220:221], v[162:163] op_sel_hi:[1,0,1] neg_lo:[0,0,1]
	v_pk_mul_f32 v[42:43], v[42:43], v[234:235]
	v_pk_mul_f32 v[162:163], v[44:45], v[222:223] op_sel:[1,1] op_sel_hi:[0,1]
	v_pk_fma_f32 v[44:45], v[44:45], v[222:223], v[162:163] op_sel_hi:[1,0,1] neg_lo:[0,0,1]
	v_pk_mul_f32 v[44:45], v[44:45], v[234:235]
	v_cvt_pk_bf16_f32 v164, v46, v47
	v_cvt_pk_bf16_f32 v165, v48, v49
	v_cvt_pk_bf16_f32 v166, v42, v43
	v_cvt_pk_bf16_f32 v167, v44, v45
	global_store_dwordx4 v230, v[164:167], s[10:11] offset:0
	v_pk_mul_f32 v[162:163], v[38:39], v[216:217] op_sel:[1,1] op_sel_hi:[0,1]
	v_pk_fma_f32 v[38:39], v[38:39], v[216:217], v[162:163] op_sel_hi:[1,0,1] neg_lo:[0,0,1]
	v_pk_mul_f32 v[38:39], v[38:39], v[234:235]
	v_pk_mul_f32 v[162:163], v[40:41], v[218:219] op_sel:[1,1] op_sel_hi:[0,1]
	v_pk_fma_f32 v[40:41], v[40:41], v[218:219], v[162:163] op_sel_hi:[1,0,1] neg_lo:[0,0,1]
	v_pk_mul_f32 v[40:41], v[40:41], v[234:235]
	v_pk_mul_f32 v[162:163], v[34:35], v[220:221] op_sel:[1,1] op_sel_hi:[0,1]
	v_pk_fma_f32 v[34:35], v[34:35], v[220:221], v[162:163] op_sel_hi:[1,0,1] neg_lo:[0,0,1]
	v_pk_mul_f32 v[34:35], v[34:35], v[234:235]
	v_pk_mul_f32 v[162:163], v[36:37], v[222:223] op_sel:[1,1] op_sel_hi:[0,1]
	v_pk_fma_f32 v[36:37], v[36:37], v[222:223], v[162:163] op_sel_hi:[1,0,1] neg_lo:[0,0,1]
	v_pk_mul_f32 v[36:37], v[36:37], v[234:235]
	v_cvt_pk_bf16_f32 v168, v38, v39
	v_cvt_pk_bf16_f32 v169, v40, v41
	v_cvt_pk_bf16_f32 v170, v34, v35
	v_cvt_pk_bf16_f32 v171, v36, v37
	global_store_dwordx4 v230, v[168:171], s[10:11] offset:256
	s_add_u32 s10, s6, 0x190000
	s_addc_u32 s11, s7, 0
	v_pk_mul_f32 v[30:31], v[30:31], v[158:159] op_sel_hi:[1,0]
	v_pk_mul_f32 v[32:33], v[32:33], v[158:159] op_sel_hi:[1,0]
	v_pk_mul_f32 v[26:27], v[26:27], v[158:159] op_sel_hi:[1,0]
	v_pk_mul_f32 v[28:29], v[28:29], v[158:159] op_sel_hi:[1,0]
	v_pk_mul_f32 v[22:23], v[22:23], v[158:159] op_sel_hi:[1,0]
	v_pk_mul_f32 v[24:25], v[24:25], v[158:159] op_sel_hi:[1,0]
	v_pk_mul_f32 v[18:19], v[18:19], v[158:159] op_sel_hi:[1,0]
	v_pk_mul_f32 v[20:21], v[20:21], v[158:159] op_sel_hi:[1,0]
	s_waitcnt vmcnt(14)
; #define GAS __attribute__((address_space(1)))
; __device__ __forceinline__ unsigned cvt_pk_bf16(float lo, float hi) { unsigned r; asm volatile("v_cvt_pk_bf16_f32 %0, %1, %2" : "=v"(r) : "v"(lo), "v"(hi)); return r; }
;     __device__ __forceinline__ void operator()(const f32x4 (&acc)[2][2][4][2], const Unit& u, int wr, int wc, int fr, int fq, const PG8_LAS float* tab) const {
;     ...
;                     f32x4 v0 = acc[ai][bj][m][0] * rs, v1 = acc[ai][bj][m][1] * rs;
;                     if (is_rope) {
;                         const GAS f32x4* rp = (const GAS f32x4*)((const GAS f32x2*)rope + (size_t)pos * 32 + ((col0 & 63) >> 1));
;                         const f32x4 cs0 = rp[0], cs1 = rp[1];
;                         f32x4 o0, o1;
;                         o0[0] = v0[0] * cs0[0] - v0[1] * cs0[1]; o0[1] = v0[1] * cs0[0] + v0[0] * cs0[1];
;                         o0[2] = v0[2] * cs0[2] - v0[3] * cs0[3]; o0[3] = v0[3] * cs0[2] + v0[2] * cs0[3];
;                         o1[0] = v1[0] * cs1[0] - v1[1] * cs1[1]; o1[1] = v1[1] * cs1[0] + v1[0] * cs1[1];
;                         o1[2] = v1[2] * cs1[2] - v1[3] * cs1[3]; o1[3] = v1[3] * cs1[2] + v1[2] * cs1[3];
;                         v0 = o0 * qs; v1 = o1 * qs;
;                     }
;                     {
;                         u32x4 w; w.x = cvt_pk_bf16(v0[0], v0[1]); w.y = cvt_pk_bf16(v0[2], v0[3]); w.z = cvt_pk_bf16(v1[0], v1[1]); w.w = cvt_pk_bf16(v1[2], v1[3]);
;                         *(GAS u32x4*)(rowp + col0) = w;
;                     }
	v_pk_mul_f32 v[162:163], v[30:31], v[224:225] op_sel:[1,1] op_sel_hi:[0,1]
	v_pk_fma_f32 v[30:31], v[30:31], v[224:225], v[162:163] op_sel_hi:[1,0,1] neg_lo:[0,0,1]
	v_pk_mul_f32 v[30:31], v[30:31], v[234:235]
	v_pk_mul_f32 v[162:163], v[32:33], v[226:227] op_sel:[1,1] op_sel_hi:[0,1]
	v_pk_fma_f32 v[32:33], v[32:33], v[226:227], v[162:163] op_sel_hi:[1,0,1] neg_lo:[0,0,1]
	v_pk_mul_f32 v[32:33], v[32:33], v[234:235]
	v_pk_mul_f32 v[162:163], v[26:27], v[240:241] op_sel:[1,1] op_sel_hi:[0,1]
	v_pk_fma_f32 v[26:27], v[26:27], v[240:241], v[162:163] op_sel_hi:[1,0,1] neg_lo:[0,0,1]
	v_pk_mul_f32 v[26:27], v[26:27], v[234:235]
	v_pk_mul_f32 v[162:163], v[28:29], v[242:243] op_sel:[1,1] op_sel_hi:[0,1]
	v_pk_fma_f32 v[28:29], v[28:29], v[242:243], v[162:163] op_sel_hi:[1,0,1] neg_lo:[0,0,1]
	v_pk_mul_f32 v[28:29], v[28:29], v[234:235]
	v_cvt_pk_bf16_f32 v164, v30, v31
	v_cvt_pk_bf16_f32 v165, v32, v33
	v_cvt_pk_bf16_f32 v166, v26, v27
	v_cvt_pk_bf16_f32 v167, v28, v29
	global_store_dwordx4 v230, v[164:167], s[10:11] offset:0
	v_pk_mul_f32 v[162:163], v[22:23], v[224:225] op_sel:[1,1] op_sel_hi:[0,1]
	v_pk_fma_f32 v[22:23], v[22:23], v[224:225], v[162:163] op_sel_hi:[1,0,1] neg_lo:[0,0,1]
	v_pk_mul_f32 v[22:23], v[22:23], v[234:235]
	v_pk_mul_f32 v[162:163], v[24:25], v[226:227] op_sel:[1,1] op_sel_hi:[0,1]
	v_pk_fma_f32 v[24:25], v[24:25], v[226:227], v[162:163] op_sel_hi:[1,0,1] neg_lo:[0,0,1]
	v_pk_mul_f32 v[24:25], v[24:25], v[234:235]
	v_pk_mul_f32 v[162:163], v[18:19], v[240:241] op_sel:[1,1] op_sel_hi:[0,1]
	v_pk_fma_f32 v[18:19], v[18:19], v[240:241], v[162:163] op_sel_hi:[1,0,1] neg_lo:[0,0,1]
	v_pk_mul_f32 v[18:19], v[18:19], v[234:235]
	v_pk_mul_f32 v[162:163], v[20:21], v[242:243] op_sel:[1,1] op_sel_hi:[0,1]
	v_pk_fma_f32 v[20:21], v[20:21], v[242:243], v[162:163] op_sel_hi:[1,0,1] neg_lo:[0,0,1]
	v_pk_mul_f32 v[20:21], v[20:21], v[234:235]
	v_cvt_pk_bf16_f32 v168, v22, v23
	v_cvt_pk_bf16_f32 v169, v24, v25
	v_cvt_pk_bf16_f32 v170, v18, v19
	v_cvt_pk_bf16_f32 v171, v20, v21
	global_store_dwordx4 v230, v[168:171], s[10:11] offset:256
	s_add_u32 s10, s6, 0x1b8000
	s_addc_u32 s11, s7, 0
	v_pk_mul_f32 v[14:15], v[14:15], v[160:161] op_sel_hi:[1,0]
	v_pk_mul_f32 v[16:17], v[16:17], v[160:161] op_sel_hi:[1,0]
	v_pk_mul_f32 v[10:11], v[10:11], v[160:161] op_sel_hi:[1,0]
	v_pk_mul_f32 v[12:13], v[12:13], v[160:161] op_sel_hi:[1,0]
	v_pk_mul_f32 v[6:7], v[6:7], v[160:161] op_sel_hi:[1,0]
	v_pk_mul_f32 v[8:9], v[8:9], v[160:161] op_sel_hi:[1,0]
	v_pk_mul_f32 v[2:3], v[2:3], v[160:161] op_sel_hi:[1,0]
	v_pk_mul_f32 v[4:5], v[4:5], v[160:161] op_sel_hi:[1,0]
	s_waitcnt vmcnt(14)
	v_pk_mul_f32 v[162:163], v[14:15], v[244:245] op_sel:[1,1] op_sel_hi:[0,1]
	v_pk_fma_f32 v[14:15], v[14:15], v[244:245], v[162:163] op_sel_hi:[1,0,1] neg_lo:[0,0,1]
	v_pk_mul_f32 v[14:15], v[14:15], v[234:235]
	v_pk_mul_f32 v[162:163], v[16:17], v[246:247] op_sel:[1,1] op_sel_hi:[0,1]
	v_pk_fma_f32 v[16:17], v[16:17], v[246:247], v[162:163] op_sel_hi:[1,0,1] neg_lo:[0,0,1]
	v_pk_mul_f32 v[16:17], v[16:17], v[234:235]
	v_pk_mul_f32 v[162:163], v[10:11], v[248:249] op_sel:[1,1] op_sel_hi:[0,1]
	v_pk_fma_f32 v[10:11], v[10:11], v[248:249], v[162:163] op_sel_hi:[1,0,1] neg_lo:[0,0,1]
	v_pk_mul_f32 v[10:11], v[10:11], v[234:235]
	v_pk_mul_f32 v[162:163], v[12:13], v[250:251] op_sel:[1,1] op_sel_hi:[0,1]
	v_pk_fma_f32 v[12:13], v[12:13], v[250:251], v[162:163] op_sel_hi:[1,0,1] neg_lo:[0,0,1]
	v_pk_mul_f32 v[12:13], v[12:13], v[234:235]
	v_cvt_pk_bf16_f32 v164, v14, v15
	v_cvt_pk_bf16_f32 v165, v16, v17
	v_cvt_pk_bf16_f32 v166, v10, v11
	v_cvt_pk_bf16_f32 v167, v12, v13
	global_store_dwordx4 v230, v[164:167], s[10:11] offset:0
	v_pk_mul_f32 v[162:163], v[6:7], v[244:245] op_sel:[1,1] op_sel_hi:[0,1]
	v_pk_fma_f32 v[6:7], v[6:7], v[244:245], v[162:163] op_sel_hi:[1,0,1] neg_lo:[0,0,1]
	v_pk_mul_f32 v[6:7], v[6:7], v[234:235]
	v_pk_mul_f32 v[162:163], v[8:9], v[246:247] op_sel:[1,1] op_sel_hi:[0,1]
	v_pk_fma_f32 v[8:9], v[8:9], v[246:247], v[162:163] op_sel_hi:[1,0,1] neg_lo:[0,0,1]
	v_pk_mul_f32 v[8:9], v[8:9], v[234:235]
	v_pk_mul_f32 v[162:163], v[2:3], v[248:249] op_sel:[1,1] op_sel_hi:[0,1]
	v_pk_fma_f32 v[2:3], v[2:3], v[248:249], v[162:163] op_sel_hi:[1,0,1] neg_lo:[0,0,1]
	v_pk_mul_f32 v[2:3], v[2:3], v[234:235]
	v_pk_mul_f32 v[162:163], v[4:5], v[250:251] op_sel:[1,1] op_sel_hi:[0,1]
	v_pk_fma_f32 v[4:5], v[4:5], v[250:251], v[162:163] op_sel_hi:[1,0,1] neg_lo:[0,0,1]
	v_pk_mul_f32 v[4:5], v[4:5], v[234:235]
	v_cvt_pk_bf16_f32 v168, v6, v7
	v_cvt_pk_bf16_f32 v169, v8, v9
	v_cvt_pk_bf16_f32 v170, v2, v3
	v_cvt_pk_bf16_f32 v171, v4, v5
	global_store_dwordx4 v230, v[168:171], s[10:11] offset:256
	s_branch .LBB0_406
